# stack18: stack15 + P4 cmp pass-A second accumulator takes the C operand directly (no 16-register copy)
# speedup vs baseline: 1.0027x; 1.0025x over previous
.LBB0_1310:
	s_and_b32 s13, s11, 1
	s_mul_i32 s6, s13, 0x2400
	v_add_u32_e32 v106, s6, v200
	ds_read_b128 v[62:65], v106
	ds_read_b128 v[58:61], v106 offset:32
	ds_read_b128 v[70:73], v106 offset:4608
	ds_read_b128 v[66:69], v106 offset:4640
	s_waitcnt lgkmcnt(3)
	v_mfma_f32_32x32x16_bf16 v[18:33], v[62:65], v[94:97], v[2:17]
	ds_read_b128 v[78:81], v106 offset:64
	ds_read_b128 v[74:77], v106 offset:96
	ds_read_b128 v[110:113], v106 offset:4672
	ds_read_b128 v[106:109], v106 offset:4704
	s_cmp_gt_i32 s12, s9
	s_cselect_b64 s[6:7], -1, 0
	s_cmp_le_i32 s12, s9
	s_waitcnt lgkmcnt(5)
	v_mfma_f32_32x32x16_bf16 v[34:49], v[70:73], v[94:97], v[2:17]
	v_mfma_f32_32x32x16_bf16 v[18:33], v[58:61], v[86:89], v[18:33]
	s_waitcnt lgkmcnt(4)
	v_mfma_f32_32x32x16_bf16 v[34:49], v[66:69], v[86:89], v[34:49]
	s_waitcnt lgkmcnt(3)
	v_mfma_f32_32x32x16_bf16 v[18:33], v[78:81], v[90:93], v[18:33]
	s_waitcnt lgkmcnt(1)
	v_mfma_f32_32x32x16_bf16 v[34:49], v[110:113], v[90:93], v[34:49]
	v_mfma_f32_32x32x16_bf16 v[18:33], v[74:77], v[98:101], v[18:33]
	s_waitcnt lgkmcnt(0)
	v_mfma_f32_32x32x16_bf16 v[34:49], v[106:109], v[98:101], v[34:49]
	s_cbranch_scc1 .LBB0_1312
	v_add_u32_e32 v117, s12, v142
	v_subrev_u32_e32 v118, 63, v117
	v_cmp_lt_i32_e32 vcc, v118, v233
	s_nop 5
	v_cndmask_b32_e32 v19, v207, v19, vcc
	v_cmp_le_i32_e32 vcc, v118, v233
	s_nop 1
	v_cndmask_b32_e32 v18, v207, v18, vcc
	v_cmp_lt_i32_e32 vcc, v118, v234
	s_nop 1
	v_cndmask_b32_e32 v35, v207, v35, vcc
	v_cmp_le_i32_e32 vcc, v118, v234
	v_subrev_u32_e32 v118, 61, v117
	s_nop 0
	v_cndmask_b32_e32 v34, v207, v34, vcc
	v_cmp_le_i32_e32 vcc, v118, v233
	s_nop 1
	v_cndmask_b32_e32 v20, v207, v20, vcc
	v_cmp_le_i32_e32 vcc, v118, v234
	v_subrev_u32_e32 v118, 60, v117
	s_nop 0
	v_cndmask_b32_e32 v36, v207, v36, vcc
	v_cmp_le_i32_e32 vcc, v118, v233
	s_nop 1
	v_cndmask_b32_e32 v21, v207, v21, vcc
	v_cmp_le_i32_e32 vcc, v118, v234
	v_subrev_u32_e32 v118, 55, v117
	s_nop 0
	v_cndmask_b32_e32 v37, v207, v37, vcc
	v_cmp_le_i32_e32 vcc, v118, v233
	s_nop 1
	v_cndmask_b32_e32 v22, v207, v22, vcc
	v_cmp_le_i32_e32 vcc, v118, v234
	v_subrev_u32_e32 v118, 54, v117
	s_nop 0
	v_cndmask_b32_e32 v38, v207, v38, vcc
	v_cmp_le_i32_e32 vcc, v118, v233
	s_nop 1
	v_cndmask_b32_e32 v23, v207, v23, vcc
	v_cmp_le_i32_e32 vcc, v118, v234
	v_subrev_u32_e32 v118, 53, v117
	s_nop 0
	v_cndmask_b32_e32 v39, v207, v39, vcc
	v_cmp_le_i32_e32 vcc, v118, v233
	s_nop 1
	v_cndmask_b32_e32 v24, v207, v24, vcc
	v_cmp_le_i32_e32 vcc, v118, v234
	v_subrev_u32_e32 v118, 52, v117
	s_nop 0
	v_cndmask_b32_e32 v40, v207, v40, vcc
	v_cmp_le_i32_e32 vcc, v118, v233
	s_nop 1
	v_cndmask_b32_e32 v25, v207, v25, vcc
	v_cmp_le_i32_e32 vcc, v118, v234
	v_subrev_u32_e32 v118, 47, v117
	s_nop 0
	v_cndmask_b32_e32 v41, v207, v41, vcc
	v_cmp_le_i32_e32 vcc, v118, v233
	s_nop 1
	v_cndmask_b32_e32 v26, v207, v26, vcc
	v_cmp_le_i32_e32 vcc, v118, v234
	v_subrev_u32_e32 v118, 46, v117
	s_nop 0
	v_cndmask_b32_e32 v42, v207, v42, vcc
	v_cmp_le_i32_e32 vcc, v118, v233
	s_nop 1
	v_cndmask_b32_e32 v27, v207, v27, vcc
	v_cmp_le_i32_e32 vcc, v118, v234
	v_subrev_u32_e32 v118, 45, v117
	s_nop 0
	v_cndmask_b32_e32 v43, v207, v43, vcc
	v_cmp_le_i32_e32 vcc, v118, v233
	s_nop 1
	v_cndmask_b32_e32 v28, v207, v28, vcc
	v_cmp_le_i32_e32 vcc, v118, v234
	v_subrev_u32_e32 v118, 44, v117
	s_nop 0
	v_cndmask_b32_e32 v44, v207, v44, vcc
	v_cmp_le_i32_e32 vcc, v118, v233
	s_nop 1
	v_cndmask_b32_e32 v29, v207, v29, vcc
	v_cmp_le_i32_e32 vcc, v118, v234
	v_subrev_u32_e32 v118, 39, v117
	s_nop 0
	v_cndmask_b32_e32 v45, v207, v45, vcc
	v_cmp_le_i32_e32 vcc, v118, v233
	s_nop 1
	v_cndmask_b32_e32 v30, v207, v30, vcc
	v_cmp_le_i32_e32 vcc, v118, v234
	v_subrev_u32_e32 v118, 38, v117
	s_nop 0
	v_cndmask_b32_e32 v46, v207, v46, vcc
	v_cmp_le_i32_e32 vcc, v118, v233
	s_nop 1
	v_cndmask_b32_e32 v31, v207, v31, vcc
	v_cmp_le_i32_e32 vcc, v118, v234
	v_subrev_u32_e32 v118, 37, v117
	v_subrev_u32_e32 v117, 36, v117
	v_cndmask_b32_e32 v47, v207, v47, vcc
	v_cmp_le_i32_e32 vcc, v118, v233
	s_nop 1
	v_cndmask_b32_e32 v32, v207, v32, vcc
	v_cmp_le_i32_e32 vcc, v118, v234
	s_nop 1
	v_cndmask_b32_e32 v48, v207, v48, vcc
	v_cmp_le_i32_e32 vcc, v117, v233
	s_nop 1
	v_cndmask_b32_e32 v33, v207, v33, vcc
	v_cmp_le_i32_e32 vcc, v117, v234
	s_nop 1
	v_cndmask_b32_e32 v49, v207, v49, vcc
